# no cache invalidate at the four per-XCD barriers whose consumers only read lines this CU has not touched since the last grid barrier
# speedup vs baseline: 1.0055x; 1.0055x over previous
; __device__ __forceinline__ unsigned xb_ld(unsigned* p)              { return __hip_atomic_load(p, __ATOMIC_RELAXED, __HIP_MEMORY_SCOPE_AGENT); }
; __device__ __forceinline__ unsigned xb_add(unsigned* p, unsigned v) { return __hip_atomic_fetch_add(p, v, __ATOMIC_RELAXED, __HIP_MEMORY_SCOPE_AGENT); }
; #define XB_SPIN(cond, bar) do { unsigned _sp = 0; while (cond) { __builtin_amdgcn_s_sleep(1); \
;     if ((++_sp & 255u) == 0u) { if (xb_ld(&(bar)[XB_TMO])) break; if (_sp > XB_SPIN_CAP) { atomicAdd(&(bar)[XB_TMO], 1u); break; } } } } while (0)
; __device__ __forceinline__ void xcd_barrier(const XcdBarrier& b) {
;     ...
;             else XB_SPIN(xb_ld(&bar[XB_TOPGEN]) == tg, bar);
;             __builtin_amdgcn_fence(__ATOMIC_ACQUIRE, "agent");
;             xb_add(&bar[XB_XGEN(b.x)], 1u);
;             asm volatile("s_waitcnt vmcnt(0)" ::: "memory");
;         } else {
;             XB_SPIN(xb_ld(&bar[XB_XGEN(b.x)]) == gen, bar);
;             __builtin_amdgcn_fence(__ATOMIC_ACQUIRE, "agent");
;             asm volatile("s_waitcnt vmcnt(0)" ::: "memory");
.LBB0_184:
	s_or_b64 exec, exec, s[4:5]
	s_waitcnt vmcnt(0)
	s_nop 0
	s_waitcnt vmcnt(0)
.LBB0_185:
	s_andn2_saveexec_b64 s[2:3], s[2:3]
	s_cbranch_execz .LBB0_203
	s_waitcnt vmcnt(0) lgkmcnt(0)
	s_nop 0
	global_atomic_add v[196:197], v241, off
	s_waitcnt vmcnt(0)
